# light combination + gate-vector load no longer waited for before the residual loads (written to LDS behind vmcnt(16))
# baseline (speedup 1.0000x reference)
; #define LAS __attribute__((address_space(3)))
; __device__ __forceinline__ unsigned cvt_pk_bf16(float lo, float hi) { const cvt_f32x2_t v = {lo, hi}; const cvt_bf16x2_t b = __builtin_convertvector(v, cvt_bf16x2_t); return __builtin_bit_cast(unsigned, b); }
;     __device__ __forceinline__ void operator()(const f32x4 (&acc)[2][2][4][2], const Unit& u, int wr, int wc, int fr, int fq) const {
;     ...
;         { const int t = (wr * 4 + wc) * 64 + fq * 16 + fr;
;           if (t < 64) ((LAS f32x4*)gl)[t] = *(const f32x4*)(gate + (size_t)b * gate_ld + u.pn * 256 + 4 * t);
;           else if (t < 128 && gmn) ((LAS f32x4*)gl)[t] = *(const f32x4*)(gmn + (size_t)b * DM + u.pn * 256 + 4 * (t - 64));
;           asm volatile("s_waitcnt vmcnt(0) lgkmcnt(0)" ::: "memory"); __builtin_amdgcn_s_barrier(); asm volatile("" ::: "memory"); }
;         const LAS float* gtp = gl + wc * 32 + 8 * fq; const LAS float* gmp = gl + 256 + wc * 32 + 8 * fq;
; #pragma unroll
;         for (int ai = 0; ai < 2; ++ai) {
;             f32x4 xr[4][2][2];
; #pragma unroll
;             for (int m = 0; m < 4; ++m) { const size_t off = (size_t)(u.pm * 256 + ai * 128 + wr * 64 + m * 16 + fr) * DM + col0;
; #pragma unroll
;                 for (int bj = 0; bj < 2; ++bj)
; #pragma unroll
;                     for (int n = 0; n < 2; ++n) xr[m][bj][n] = *(const f32x4*)(xin + off + 128 * bj + 4 * n); }
;             asm volatile("" ::: "memory");
; #pragma unroll
;             for (int m = 0; m < 4; ++m) {
;                 const int row = u.pm * 256 + ai * 128 + wr * 64 + m * 16 + fr;
;                 const size_t off = (size_t)row * DM + col0;
;                 float ss = 0.f;
; #pragma unroll
;                 for (int bj = 0; bj < 2; ++bj) {
;                     const f32x4 xo0 = xr[m][bj][0] + *(const LAS f32x4*)(gtp + 128 * bj) * acc[ai][bj][m][0], xo1 = xr[m][bj][1] + *(const LAS f32x4*)(gtp + 128 * bj + 4) * acc[ai][bj][m][1];
;                     *(f32x4*)(xout + off + 128 * bj) = xo0; *(f32x4*)(xout + off + 128 * bj + 4) = xo1;
;                     if (gmn) { ss += sq4(xo0) + sq4(xo1); const f32x4 a = xo0 * *(const LAS f32x4*)(gmp + 128 * bj), c = xo1 * *(const LAS f32x4*)(gmp + 128 * bj + 4);
;                         u32x4 w; w.x = cvt_pk_bf16(a[0], a[1]); w.y = cvt_pk_bf16(a[2], a[3]); w.z = cvt_pk_bf16(c[0], c[1]); w.w = cvt_pk_bf16(c[2], c[3]); *(u32x4*)(AX + off + 128 * bj) = w; }
.LBB0_215:
	global_load_dwordx4 v[216:219], v[104:105], off
	v_lshl_add_u32 v220, v107, 4, 0
	v_add_u32_e32 v220, 0x20400, v220
.LBB0_216:
	s_or_b64 exec, exec, s[46:47]
	s_or_b32 s44, s44, s58
	v_lshl_add_u32 v224, v250, 3, s44
	s_lshl_b32 s44, s77, 8
	s_add_i32 s44, s44, s7
	v_add_u32_e32 v226, s44, v106
	v_readlane_b32 s44, v255, 46
	v_lshlrev_b32_e32 v104, 5, v250
	v_ashrrev_i32_e32 v225, 31, v224
	v_readlane_b32 s45, v255, 47
	v_ashrrev_i32_e32 v227, 31, v226
	v_add_u32_e32 v249, s87, v104
	v_add_u32_e32 v192, s8, v104
	v_lshl_add_u64 v[228:229], v[224:225], 2, s[44:45]
	v_lshlrev_b64 v[104:105], 12, v[226:227]
	v_add_u32_e32 v234, 16, v226
	v_lshl_add_u64 v[104:105], v[228:229], 0, v[104:105]
	v_ashrrev_i32_e32 v235, 31, v234
	global_load_dwordx4 v[194:197], v[104:105], off offset:16
	global_load_dwordx4 v[198:201], v[104:105], off
	global_load_dwordx4 v[184:187], v[104:105], off offset:528
	global_load_dwordx4 v[188:191], v[104:105], off offset:512
	v_lshlrev_b64 v[104:105], 12, v[234:235]
	v_add_u32_e32 v232, 32, v226
	v_lshl_add_u64 v[104:105], v[228:229], 0, v[104:105]
	v_ashrrev_i32_e32 v233, 31, v232
	global_load_dwordx4 v[176:179], v[104:105], off offset:16
	global_load_dwordx4 v[180:183], v[104:105], off
	global_load_dwordx4 v[168:171], v[104:105], off offset:528
	global_load_dwordx4 v[172:175], v[104:105], off offset:512
	v_lshlrev_b64 v[104:105], 12, v[232:233]
	v_add_u32_e32 v230, 48, v226
	v_lshl_add_u64 v[104:105], v[228:229], 0, v[104:105]
	v_ashrrev_i32_e32 v231, 31, v230
	global_load_dwordx4 v[160:163], v[104:105], off offset:16
	global_load_dwordx4 v[164:167], v[104:105], off
	global_load_dwordx4 v[152:155], v[104:105], off offset:528
	global_load_dwordx4 v[156:159], v[104:105], off offset:512
	v_lshlrev_b64 v[104:105], 12, v[230:231]
	v_lshl_add_u64 v[112:113], v[228:229], 0, v[104:105]
	global_load_dwordx4 v[136:139], v[112:113], off offset:16
	global_load_dwordx4 v[144:147], v[112:113], off
	global_load_dwordx4 v[104:107], v[112:113], off offset:528
	s_nop 0
	global_load_dwordx4 v[112:115], v[112:113], off offset:512
	v_lshlrev_b64 v[140:141], 10, v[226:227]
	v_lshl_add_u64 v[202:203], v[140:141], 0, v[224:225]
	s_and_saveexec_b64 s[46:47], s[56:57]
	s_cbranch_execz .Lgs_ph_skip
	s_waitcnt vmcnt(16)
	ds_write_b128 v220, v[216:219]
.Lgs_ph_skip:
	s_or_b64 exec, exec, s[46:47]
	s_waitcnt vmcnt(16) lgkmcnt(0)
	s_barrier
	ds_read_b128 v[148:151], v249
	ds_read_b128 v[140:143], v249 offset:16
	v_lshl_add_u64 v[236:237], v[202:203], 2, s[20:21]
	v_lshl_add_u32 v236, v202, 2, v246
	v_mov_b32_e32 v251, 0
	s_andn2_b64 vcc, exec, s[40:41]
	v_lshl_add_u64 v[238:239], v[202:203], 1, s[16:17]
	v_lshl_add_u64 v[238:239], v[204:205], 0, v[238:239]
	s_waitcnt vmcnt(0) lgkmcnt(0)
	v_pk_fma_f32 v[128:129], v[128:129], v[140:141], v[194:195]
	v_cndmask_b32_e64 v194, 0, 1, s[40:41]
	v_pk_fma_f32 v[134:135], v[134:135], v[150:151], v[200:201]
	v_pk_fma_f32 v[132:133], v[132:133], v[148:149], v[198:199]
	v_pk_fma_f32 v[130:131], v[130:131], v[142:143], v[196:197]
	v_cmp_ne_u32_e64 s[46:47], 1, v194
	ds_write_b128 v208, v[132:135]
	ds_write_b128 v208, v[128:131] offset:16
	ds_read_b128 v[216:219], v210
	ds_read_b128 v[220:223], v210 offset:1152
	s_waitcnt lgkmcnt(0)
	global_store_dwordx4 v236, v[216:219], s[20:21]
	global_store_dwordx4 v236, v[220:223], s[100:101]
	s_cbranch_vccnz .LBB0_218
	v_mov_b32_e32 v196, v133
	v_mov_b32_e32 v197, v129
	v_mov_b32_e32 v194, v132
	v_mov_b32_e32 v195, v128
	v_pk_mul_f32 v[196:197], v[196:197], v[196:197]
	v_mov_b32_e32 v198, v135
	v_mov_b32_e32 v199, v131
	v_pk_fma_f32 v[194:195], v[194:195], v[194:195], v[196:197]
	v_mov_b32_e32 v196, v134
	v_mov_b32_e32 v197, v130
	v_pk_mul_f32 v[198:199], v[198:199], v[198:199]
	s_nop 0
	v_pk_fma_f32 v[196:197], v[196:197], v[196:197], v[198:199]
	s_nop 0
	v_pk_add_f32 v[194:195], v[194:195], v[196:197]
	s_nop 0
	v_add_f32_e32 v251, v194, v195
	ds_read_b128 v[194:197], v192
	ds_read_b128 v[198:201], v192 offset:16
	s_waitcnt lgkmcnt(1)
	v_pk_mul_f32 v[134:135], v[134:135], v[196:197]
	v_pk_mul_f32 v[132:133], v[132:133], v[194:195]
	s_waitcnt lgkmcnt(0)
	v_pk_mul_f32 v[194:195], v[130:131], v[200:201]
	v_pk_mul_f32 v[130:131], v[128:129], v[198:199]
	v_cvt_pk_bf16_f32 v128, v132, v133
	v_cvt_pk_bf16_f32 v129, v134, v135
	v_cvt_pk_bf16_f32 v130, v130, v131
	v_cvt_pk_bf16_f32 v131, v194, v195
	ds_bpermute_b32 v128, v206, v128
	ds_bpermute_b32 v129, v206, v129
	ds_bpermute_b32 v130, v206, v130
	ds_bpermute_b32 v131, v206, v131
	s_waitcnt lgkmcnt(0)
	global_store_dwordx4 v[238:239], v[128:131], off

; #define LAS __attribute__((address_space(3)))
; __device__ __forceinline__ unsigned cvt_pk_bf16(float lo, float hi) { const cvt_f32x2_t v = {lo, hi}; const cvt_bf16x2_t b = __builtin_convertvector(v, cvt_bf16x2_t); return __builtin_bit_cast(unsigned, b); }
;     __device__ __forceinline__ void operator()(const f32x4 (&acc)[2][2][4][2], const Unit& u, int wr, int wc, int fr, int fq) const {
;     ...
;         { const int t = (wr * 4 + wc) * 64 + fq * 16 + fr;
;           if (t < 64) ((LAS f32x4*)gl)[t] = *(const f32x4*)(gate + (size_t)b * gate_ld + u.pn * 256 + 4 * t);
;           else if (t < 128 && gmn) ((LAS f32x4*)gl)[t] = *(const f32x4*)(gmn + (size_t)b * DM + u.pn * 256 + 4 * (t - 64));
;           asm volatile("s_waitcnt vmcnt(0) lgkmcnt(0)" ::: "memory"); __builtin_amdgcn_s_barrier(); asm volatile("" ::: "memory"); }
;         const LAS float* gtp = gl + wc * 32 + 8 * fq; const LAS float* gmp = gl + 256 + wc * 32 + 8 * fq;
; #pragma unroll
;         for (int ai = 0; ai < 2; ++ai) {
;             f32x4 xr[4][2][2];
; #pragma unroll
;             for (int m = 0; m < 4; ++m) { const size_t off = (size_t)(u.pm * 256 + ai * 128 + wr * 64 + m * 16 + fr) * DM + col0;
; #pragma unroll
;                 for (int bj = 0; bj < 2; ++bj)
; #pragma unroll
;                     for (int n = 0; n < 2; ++n) xr[m][bj][n] = *(const f32x4*)(xin + off + 128 * bj + 4 * n); }
;             asm volatile("" ::: "memory");
; #pragma unroll
;             for (int m = 0; m < 4; ++m) {
;                 const int row = u.pm * 256 + ai * 128 + wr * 64 + m * 16 + fr;
;                 const size_t off = (size_t)row * DM + col0;
;                 float ss = 0.f;
; #pragma unroll
;                 for (int bj = 0; bj < 2; ++bj) {
;                     const f32x4 xo0 = xr[m][bj][0] + *(const LAS f32x4*)(gtp + 128 * bj) * acc[ai][bj][m][0], xo1 = xr[m][bj][1] + *(const LAS f32x4*)(gtp + 128 * bj + 4) * acc[ai][bj][m][1];
;                     *(f32x4*)(xout + off + 128 * bj) = xo0; *(f32x4*)(xout + off + 128 * bj + 4) = xo1;
;                     if (gmn) { ss += sq4(xo0) + sq4(xo1); const f32x4 a = xo0 * *(const LAS f32x4*)(gmp + 128 * bj), c = xo1 * *(const LAS f32x4*)(gmp + 128 * bj + 4);
;                         u32x4 w; w.x = cvt_pk_bf16(a[0], a[1]); w.y = cvt_pk_bf16(a[2], a[3]); w.z = cvt_pk_bf16(c[0], c[1]); w.w = cvt_pk_bf16(c[2], c[3]); *(u32x4*)(AX + off + 128 * bj) = w; }
.LBB0_323:
	s_or_b64 exec, exec, s[46:47]
	s_or_b32 s44, s44, s9
	v_lshl_add_u32 v224, v250, 3, s44
	s_lshl_b32 s44, s77, 8
	s_add_i32 s44, s44, s8
	v_add_u32_e32 v226, s44, v106
	v_readlane_b32 s44, v255, 48
	v_lshlrev_b32_e32 v104, 5, v250
	v_ashrrev_i32_e32 v225, 31, v224
	v_readlane_b32 s45, v255, 49
	v_ashrrev_i32_e32 v227, 31, v226
	v_add_u32_e32 v249, s41, v104
	v_add_u32_e32 v192, s4, v104
	v_lshl_add_u64 v[228:229], v[224:225], 2, s[44:45]
	v_lshlrev_b64 v[104:105], 12, v[226:227]
	v_add_u32_e32 v234, 16, v226
	v_lshl_add_u64 v[104:105], v[228:229], 0, v[104:105]
	v_ashrrev_i32_e32 v235, 31, v234
	global_load_dwordx4 v[194:197], v[104:105], off offset:16
	global_load_dwordx4 v[198:201], v[104:105], off
	global_load_dwordx4 v[184:187], v[104:105], off offset:528
	global_load_dwordx4 v[188:191], v[104:105], off offset:512
	v_lshlrev_b64 v[104:105], 12, v[234:235]
	v_add_u32_e32 v232, 32, v226
	v_lshl_add_u64 v[104:105], v[228:229], 0, v[104:105]
	v_ashrrev_i32_e32 v233, 31, v232
	global_load_dwordx4 v[176:179], v[104:105], off offset:16
	global_load_dwordx4 v[180:183], v[104:105], off
	global_load_dwordx4 v[168:171], v[104:105], off offset:528
	global_load_dwordx4 v[172:175], v[104:105], off offset:512
	v_lshlrev_b64 v[104:105], 12, v[232:233]
	v_add_u32_e32 v230, 48, v226
	v_lshl_add_u64 v[104:105], v[228:229], 0, v[104:105]
	v_ashrrev_i32_e32 v231, 31, v230
	global_load_dwordx4 v[160:163], v[104:105], off offset:16
	global_load_dwordx4 v[164:167], v[104:105], off
	global_load_dwordx4 v[152:155], v[104:105], off offset:528
	global_load_dwordx4 v[156:159], v[104:105], off offset:512
	v_lshlrev_b64 v[104:105], 12, v[230:231]
	v_lshl_add_u64 v[112:113], v[228:229], 0, v[104:105]
	global_load_dwordx4 v[136:139], v[112:113], off offset:16
	global_load_dwordx4 v[144:147], v[112:113], off
	global_load_dwordx4 v[104:107], v[112:113], off offset:528
	s_nop 0
	global_load_dwordx4 v[112:115], v[112:113], off offset:512
	v_lshlrev_b64 v[140:141], 10, v[226:227]
	v_lshl_add_u64 v[202:203], v[140:141], 0, v[224:225]
	s_and_saveexec_b64 s[46:47], s[56:57]
	s_cbranch_execz .Lgs_pf_skip
	s_waitcnt vmcnt(16)
	ds_write_b128 v220, v[216:219]
.Lgs_pf_skip:
	s_or_b64 exec, exec, s[46:47]
	s_waitcnt vmcnt(16) lgkmcnt(0)
	s_barrier
	ds_read_b128 v[148:151], v249
	ds_read_b128 v[140:143], v249 offset:16
	v_lshl_add_u64 v[236:237], v[202:203], 2, s[6:7]
	v_lshl_add_u32 v236, v202, 2, v246
	v_mov_b32_e32 v251, 0
	s_andn2_b64 vcc, exec, s[38:39]
	v_lshl_add_u64 v[238:239], v[202:203], 1, s[16:17]
	v_lshl_add_u64 v[238:239], v[204:205], 0, v[238:239]
	s_waitcnt vmcnt(0) lgkmcnt(0)
	v_pk_fma_f32 v[128:129], v[128:129], v[140:141], v[194:195]
	v_cndmask_b32_e64 v194, 0, 1, s[38:39]
	v_pk_fma_f32 v[134:135], v[134:135], v[150:151], v[200:201]
	v_pk_fma_f32 v[132:133], v[132:133], v[148:149], v[198:199]
	v_pk_fma_f32 v[130:131], v[130:131], v[142:143], v[196:197]
	v_cmp_ne_u32_e64 s[46:47], 1, v194
	ds_write_b128 v208, v[132:135]
	ds_write_b128 v208, v[128:131] offset:16
	ds_read_b128 v[216:219], v210
	ds_read_b128 v[220:223], v210 offset:1152
	s_waitcnt lgkmcnt(0)
	global_store_dwordx4 v236, v[216:219], s[6:7]
	global_store_dwordx4 v236, v[220:223], s[100:101]
	s_cbranch_vccnz .LBB0_325
	v_mov_b32_e32 v196, v133
	v_mov_b32_e32 v197, v129
	v_mov_b32_e32 v194, v132
	v_mov_b32_e32 v195, v128
	v_pk_mul_f32 v[196:197], v[196:197], v[196:197]
	v_mov_b32_e32 v198, v135
	v_mov_b32_e32 v199, v131
	v_pk_fma_f32 v[194:195], v[194:195], v[194:195], v[196:197]
	v_mov_b32_e32 v196, v134
	v_mov_b32_e32 v197, v130
	v_pk_mul_f32 v[198:199], v[198:199], v[198:199]
	s_nop 0
	v_pk_fma_f32 v[196:197], v[196:197], v[196:197], v[198:199]
	s_nop 0
	v_pk_add_f32 v[194:195], v[194:195], v[196:197]
	s_nop 0
	v_add_f32_e32 v251, v194, v195
	ds_read_b128 v[194:197], v192
	ds_read_b128 v[198:201], v192 offset:16
	s_waitcnt lgkmcnt(1)
	v_pk_mul_f32 v[134:135], v[134:135], v[196:197]
	v_pk_mul_f32 v[132:133], v[132:133], v[194:195]
	s_waitcnt lgkmcnt(0)
	v_pk_mul_f32 v[194:195], v[130:131], v[200:201]
	v_pk_mul_f32 v[130:131], v[128:129], v[198:199]
	v_cvt_pk_bf16_f32 v128, v132, v133
	v_cvt_pk_bf16_f32 v129, v134, v135
	v_cvt_pk_bf16_f32 v130, v130, v131
	v_cvt_pk_bf16_f32 v131, v194, v195
	ds_bpermute_b32 v128, v206, v128
	ds_bpermute_b32 v129, v206, v129
	ds_bpermute_b32 v130, v206, v130
	ds_bpermute_b32 v131, v206, v131
	s_waitcnt lgkmcnt(0)
	global_store_dwordx4 v[238:239], v[128:131], off
